# layer-1 in-projection skew reduced to 2 sleep quanta
# baseline (speedup 1.0000x reference)
.Lcw_sleep:
	s_sleep 0x7f
	s_sleep 0x7f
.LBB0_243:
	s_add_u32 s16, s96, s0
	s_addc_u32 s17, s97, s1
	s_add_u32 s26, s16, 0xb000000
	v_readlane_b32 s2, v253, 28
	s_addc_u32 s27, s17, 0
	v_readlane_b32 s3, v253, 29
	s_add_u32 s28, s16, 0xf000000
	v_mov_b32_e32 v8, v197
	v_cndmask_b32_e64 v0, 0, 1, s[2:3]
	s_addc_u32 s29, s17, 0
	s_barrier
	v_cmp_ne_u32_e64 s[0:1], 1, v0
	s_andn2_b64 vcc, exec, s[2:3]
	v_readfirstlane_b32 s30, v8
	s_cbranch_vccnz .LBB0_245
	v_readlane_b32 s2, v253, 31
	s_add_u32 s8, s26, s2
	s_addc_u32 s9, s27, 0
	v_readlane_b32 s2, v253, 33
	s_add_u32 s10, s28, s2
	s_addc_u32 s11, s29, 0
	v_readlane_b32 s35, v253, 30
	v_readlane_b32 s3, v253, 32
